# cand G + grid-barrier spin loops poll without s_sleep between polls
# speedup vs baseline: 1.0048x; 1.0041x over previous
.LBB0_267:
	s_nop 0
	global_load_dword v2, v0, s[2:3] offset:32 sc1
	s_waitcnt vmcnt(0)
	v_and_b32_e32 v2, 0xffff0000, v2
	v_cmp_ne_u32_e32 vcc, v2, v1
	s_or_b64 s[4:5], vcc, s[4:5]
	s_andn2_b64 exec, exec, s[4:5]
	s_cbranch_execnz .LBB0_267

.LBB0_274:
	global_load_dword v15, v16, s[92:93] offset:1024 sc1
	s_waitcnt lgkmcnt(0)
	global_load_dword v0, v16, s[92:93] offset:1280 sc1
	global_load_dword v1, v16, s[92:93] offset:1536 sc1
	global_load_dword v2, v16, s[92:93] offset:1792 sc1
	global_load_dword v3, v16, s[92:93] offset:2048 sc1
	global_load_dword v4, v16, s[92:93] offset:2304 sc1
	global_load_dword v5, v16, s[92:93] offset:2560 sc1
	global_load_dword v6, v16, s[92:93] offset:2816 sc1
	global_load_dword v7, v16, s[92:93] offset:3072 sc1
	global_load_dword v8, v16, s[92:93] offset:3328 sc1
	global_load_dword v9, v16, s[92:93] offset:3584 sc1
	global_load_dword v10, v16, s[92:93] offset:3840 sc1
	global_load_dword v11, v16, s[2:3] sc1
	global_load_dword v12, v16, s[4:5] sc1
	global_load_dword v13, v16, s[6:7] sc1
	global_load_dword v14, v16, s[8:9] sc1
	s_mov_b64 s[10:11], -1
	s_mov_b64 s[12:13], -1
	s_waitcnt vmcnt(14)
	v_add_u32_e32 v17, v0, v15
	s_waitcnt vmcnt(13)
	v_add_u32_e32 v17, v17, v1
	s_waitcnt vmcnt(12)
	v_add_u32_e32 v17, v17, v2
	s_waitcnt vmcnt(11)
	v_add_u32_e32 v17, v17, v3
	s_waitcnt vmcnt(10)
	v_add_u32_e32 v17, v17, v4
	s_waitcnt vmcnt(9)
	v_add_u32_e32 v17, v17, v5
	s_waitcnt vmcnt(8)
	v_add_u32_e32 v17, v17, v6
	s_waitcnt vmcnt(7)
	v_add_u32_e32 v17, v17, v7
	s_waitcnt vmcnt(6)
	v_add_u32_e32 v17, v17, v8
	s_waitcnt vmcnt(5)
	v_add_u32_e32 v17, v17, v9
	s_waitcnt vmcnt(4)
	v_add_u32_e32 v17, v17, v10
	s_waitcnt vmcnt(3)
	v_add_u32_e32 v17, v17, v11
	s_waitcnt vmcnt(2)
	v_add_u32_e32 v17, v17, v12
	s_waitcnt vmcnt(1)
	v_add_u32_e32 v17, v17, v13
	s_waitcnt vmcnt(0)
	v_add_u32_e32 v17, v17, v14
	v_cmp_eq_u32_e32 vcc, s17, v17
	s_cbranch_vccnz .LBB0_273
	s_and_b32 s10, s18, 0xff
	s_cmp_eq_u32 s10, 0
	s_mov_b64 s[10:11], -1
	s_mov_b64 s[14:15], -1
	s_nop 0
	s_cbranch_scc1 .LBB0_278
	s_and_b64 vcc, exec, s[14:15]
	s_cbranch_vccz .LBB0_273

.LBB0_292:
	s_and_b32 s14, s18, 0xff
	s_mov_b64 s[12:13], -1
	s_cmp_lg_u32 s14, 0
	s_mov_b64 s[16:17], -1
	s_nop 0
	s_cbranch_scc0 .LBB0_295
	s_and_b64 vcc, exec, s[16:17]
	s_cbranch_vccz .LBB0_291

.LBB0_309:
	s_and_b32 s14, s21, 0xff
	s_cmp_lg_u32 s14, 0
	s_mov_b64 s[16:17], -1
	s_nop 0
	s_cbranch_scc0 .LBB0_312
	s_mov_b64 s[18:19], -1
	s_and_b64 vcc, exec, s[16:17]
	s_cbranch_vccz .LBB0_308

.LBB0_628:
	v_readlane_b32 s2, v253, 7
	v_readlane_b32 s3, v253, 8
	global_load_dword v12, v1, s[20:21] offset:1024 sc1
	global_load_dword v0, v1, s[20:21] offset:1280 sc1
	s_waitcnt lgkmcnt(0)
	global_load_dword v2, v1, s[20:21] offset:1536 sc1
	global_load_dword v3, v1, s[20:21] offset:1792 sc1
	global_load_dword v4, v1, s[20:21] offset:2048 sc1
	global_load_dword v5, v1, s[20:21] offset:2304 sc1
	global_load_dword v6, v1, s[20:21] offset:2560 sc1
	global_load_dword v7, v1, s[20:21] offset:2816 sc1
	global_load_dword v8, v1, s[20:21] offset:3072 sc1
	global_load_dword v9, v1, s[20:21] offset:3328 sc1
	global_load_dword v10, v1, s[20:21] offset:3584 sc1
	global_load_dword v11, v1, s[20:21] offset:3840 sc1
	global_load_dword v13, v1, s[2:3] sc1
	v_readlane_b32 s2, v253, 9
	v_readlane_b32 s3, v253, 10
	v_readlane_b32 s4, v253, 4
	s_waitcnt vmcnt(11)
	v_add_u32_e32 v17, v0, v12
	s_nop 1
	global_load_dword v14, v1, s[2:3] sc1
	v_readlane_b32 s2, v253, 11
	v_readlane_b32 s3, v253, 12
	s_waitcnt vmcnt(11)
	v_add_u32_e32 v17, v17, v2
	s_waitcnt vmcnt(10)
	v_add_u32_e32 v17, v17, v3
	s_waitcnt vmcnt(9)
	v_add_u32_e32 v17, v17, v4
	s_waitcnt vmcnt(8)
	v_add_u32_e32 v17, v17, v5
	s_waitcnt vmcnt(7)
	v_add_u32_e32 v17, v17, v6
	global_load_dword v15, v1, s[2:3] sc1
	v_readlane_b32 s2, v253, 13
	v_readlane_b32 s3, v253, 14
	s_waitcnt vmcnt(7)
	v_add_u32_e32 v17, v17, v7
	s_waitcnt vmcnt(6)
	v_add_u32_e32 v17, v17, v8
	s_waitcnt vmcnt(5)
	v_add_u32_e32 v17, v17, v9
	s_waitcnt vmcnt(4)
	v_add_u32_e32 v17, v17, v10
	s_waitcnt vmcnt(3)
	v_add_u32_e32 v17, v17, v11
	global_load_dword v16, v1, s[2:3] sc1
	s_waitcnt vmcnt(3)
	v_add_u32_e32 v17, v17, v13
	s_mov_b64 s[2:3], -1
	s_waitcnt vmcnt(2)
	v_add_u32_e32 v17, v17, v14
	s_waitcnt vmcnt(1)
	v_add_u32_e32 v17, v17, v15
	s_waitcnt vmcnt(0)
	v_add_u32_e32 v17, v17, v16
	v_cmp_eq_u32_e32 vcc, s4, v17
	s_mov_b64 s[4:5], -1
	s_cbranch_vccnz .LBB0_627
	s_and_b32 s2, s9, 0xff
	s_cmp_eq_u32 s2, 0
	s_mov_b64 s[2:3], -1
	s_mov_b64 s[6:7], -1
	s_nop 0
	s_cbranch_scc1 .LBB0_632
	s_and_b64 vcc, exec, s[6:7]
	s_cbranch_vccz .LBB0_627

.LBB0_646:
	s_and_b32 s14, s19, 0xff
	s_mov_b64 s[12:13], -1
	s_cmp_lg_u32 s14, 0
	s_mov_b64 s[16:17], -1
	s_nop 0
	s_cbranch_scc0 .LBB0_649
	s_and_b64 vcc, exec, s[16:17]
	s_cbranch_vccz .LBB0_645

.LBB0_663:
	s_and_b32 s12, s16, 0xff
	s_mov_b64 s[10:11], -1
	s_cmp_lg_u32 s12, 0
	s_mov_b64 s[14:15], -1
	s_nop 0
	s_cbranch_scc0 .LBB0_666
	s_and_b64 vcc, exec, s[14:15]
	s_cbranch_vccz .LBB0_662

.LBB0_951:
	v_readlane_b32 s2, v253, 7
	v_readlane_b32 s3, v253, 8
	global_load_dword v12, v1, s[92:93] offset:1024 sc1
	global_load_dword v0, v1, s[92:93] offset:1280 sc1
	s_waitcnt lgkmcnt(0)
	global_load_dword v2, v1, s[92:93] offset:1536 sc1
	global_load_dword v3, v1, s[92:93] offset:1792 sc1
	global_load_dword v4, v1, s[92:93] offset:2048 sc1
	global_load_dword v5, v1, s[92:93] offset:2304 sc1
	global_load_dword v6, v1, s[92:93] offset:2560 sc1
	global_load_dword v7, v1, s[92:93] offset:2816 sc1
	global_load_dword v8, v1, s[92:93] offset:3072 sc1
	global_load_dword v9, v1, s[92:93] offset:3328 sc1
	global_load_dword v10, v1, s[92:93] offset:3584 sc1
	global_load_dword v11, v1, s[92:93] offset:3840 sc1
	global_load_dword v13, v1, s[2:3] sc1
	v_readlane_b32 s2, v253, 9
	v_readlane_b32 s3, v253, 10
	v_readlane_b32 s4, v253, 4
	s_waitcnt vmcnt(11)
	v_add_u32_e32 v17, v0, v12
	s_nop 1
	global_load_dword v14, v1, s[2:3] sc1
	v_readlane_b32 s2, v253, 11
	v_readlane_b32 s3, v253, 12
	s_waitcnt vmcnt(11)
	v_add_u32_e32 v17, v17, v2
	s_waitcnt vmcnt(10)
	v_add_u32_e32 v17, v17, v3
	s_waitcnt vmcnt(9)
	v_add_u32_e32 v17, v17, v4
	s_waitcnt vmcnt(8)
	v_add_u32_e32 v17, v17, v5
	s_waitcnt vmcnt(7)
	v_add_u32_e32 v17, v17, v6
	global_load_dword v15, v1, s[2:3] sc1
	v_readlane_b32 s2, v253, 13
	v_readlane_b32 s3, v253, 14
	s_waitcnt vmcnt(7)
	v_add_u32_e32 v17, v17, v7
	s_waitcnt vmcnt(6)
	v_add_u32_e32 v17, v17, v8
	s_waitcnt vmcnt(5)
	v_add_u32_e32 v17, v17, v9
	s_waitcnt vmcnt(4)
	v_add_u32_e32 v17, v17, v10
	s_waitcnt vmcnt(3)
	v_add_u32_e32 v17, v17, v11
	global_load_dword v16, v1, s[2:3] sc1
	s_waitcnt vmcnt(3)
	v_add_u32_e32 v17, v17, v13
	s_mov_b64 s[2:3], -1
	s_waitcnt vmcnt(2)
	v_add_u32_e32 v17, v17, v14
	s_waitcnt vmcnt(1)
	v_add_u32_e32 v17, v17, v15
	s_waitcnt vmcnt(0)
	v_add_u32_e32 v17, v17, v16
	v_cmp_eq_u32_e32 vcc, s4, v17
	s_mov_b64 s[4:5], -1
	s_cbranch_vccnz .LBB0_950
	s_and_b32 s2, s9, 0xff
	s_cmp_eq_u32 s2, 0
	s_mov_b64 s[2:3], -1
	s_mov_b64 s[6:7], -1
	s_nop 0
	s_cbranch_scc1 .LBB0_955
	s_and_b64 vcc, exec, s[6:7]
	s_cbranch_vccz .LBB0_950
